# scan phase: helper waves issue sample-group loads one chunk ahead, staging waits no longer cover sample stores
# speedup vs baseline: 1.0101x; 1.0101x over previous
.LBB0_1233:
	v_add_u32_e32 v0, s57, v147
	v_add_u32_e32 v6, s57, v146
	global_load_dwordx4 v[2:5], v0, s[16:17]
	s_nop 0
	global_load_dwordx4 v[6:9], v6, s[16:17]
	v_add_u32_e32 v0, s57, v145
	v_add_u32_e32 v14, s57, v144
	global_load_dwordx4 v[10:13], v0, s[16:17]
	s_nop 0
	global_load_dwordx4 v[14:17], v14, s[16:17]
	v_add_u32_e32 v0, s57, v143
	v_add_u32_e32 v22, s57, v142
	global_load_dwordx4 v[18:21], v0, s[16:17]
	s_nop 0
	global_load_dwordx4 v[22:25], v22, s[16:17]

.LBB0_1249:
	v_mov_b32_e32 v115, v138
	s_cmp_eq_u32 s0, 0
	s_cbranch_scc1 .LBB0_1258
	s_and_b32 s0, s56, 0xfc00
	s_add_i32 s0, s0, s51
	v_and_b32_e32 v54, 15, v115
	s_cmp_lg_u32 s57, 0x7f0000
	s_cbranch_scc1 .Lsu_w6
	s_waitcnt vmcnt(0)
.Lsu_w6:
	s_waitcnt vmcnt(6)
	s_cmpk_gt_i32 s0, 0x7fff
	v_cmp_gt_u32_e32 vcc, 4, v54
	s_cbranch_scc0 .Lsu_rw_fin
	s_add_i32 s2, s0, 0xffff8000
	s_bfe_u32 s1, s2, 0x30005
	s_lshr_b32 s2, s2, 6
	s_and_b32 s4, s2, 0x1fffffc
	s_add_i32 s2, s4, 0x2000
	v_pk_mul_f32 v[160:161], v[52:53], v[62:63]
	v_pk_mul_f32 v[168:169], v[46:47], v[60:61]
	v_pk_fma_f32 v[160:161], v[50:51], v[58:59], v[160:161]
	v_pk_fma_f32 v[168:169], v[48:49], v[56:57], v[168:169]
	s_nop 0
	v_pk_add_f32 v[160:161], v[168:169], v[160:161]
	s_nop 0
	v_add_f32_e32 v45, v160, v161
	s_nop 1
	v_add_f32_dpp v45, v45, v45 quad_perm:[1,0,3,2] row_mask:0xf bank_mask:0xf bound_ctrl:1
	s_nop 1
	v_add_f32_dpp v45, v45, v45 quad_perm:[2,3,0,1] row_mask:0xf bank_mask:0xf bound_ctrl:1
	s_nop 1
	v_add_f32_dpp v45, v45, v45 row_half_mirror row_mask:0xf bank_mask:0xf bound_ctrl:1
	s_nop 1
	v_add_f32_dpp v45, v45, v45 row_ror:8 row_mask:0xf bank_mask:0xf bound_ctrl:1
	s_nop 0
	v_fma_f32 v0, -v163, v45, v220
	v_mul_f32_e32 v0, v162, v0
	v_pk_mul_f32 v[60:61], v[60:61], v[0:1] op_sel_hi:[1,0]
	v_pk_mul_f32 v[62:63], v[62:63], v[0:1] op_sel_hi:[1,0]
	v_pk_fma_f32 v[46:47], v[46:47], v[162:163], v[60:61] op_sel:[0,1,0]
	v_pk_fma_f32 v[52:53], v[52:53], v[162:163], v[62:63] op_sel:[0,1,0]
	v_pk_mul_f32 v[58:59], v[58:59], v[0:1] op_sel_hi:[1,0]
	v_pk_mul_f32 v[56:57], v[56:57], v[0:1] op_sel_hi:[1,0]
	v_pk_fma_f32 v[50:51], v[50:51], v[162:163], v[58:59] op_sel:[0,1,0]
	v_pk_fma_f32 v[48:49], v[48:49], v[162:163], v[56:57] op_sel:[0,1,0]
	v_pk_mul_f32 v[56:57], v[68:69], v[46:47]
	v_pk_mul_f32 v[58:59], v[70:71], v[52:53]
	v_pk_fma_f32 v[56:57], v[48:49], v[64:65], v[56:57]
	v_pk_fma_f32 v[58:59], v[50:51], v[66:67], v[58:59]
	s_nop 0
	v_pk_add_f32 v[56:57], v[56:57], v[58:59]
	s_nop 0
	v_pk_mul_f32 v[58:59], v[78:79], v[52:53]
	v_add_f32_e32 v0, v56, v57
	v_pk_mul_f32 v[56:57], v[76:77], v[46:47]
	v_pk_fma_f32 v[58:59], v[50:51], v[74:75], v[58:59]
	v_pk_fma_f32 v[56:57], v[48:49], v[72:73], v[56:57]
	v_add_f32_dpp v0, v0, v0 quad_perm:[1,0,3,2] row_mask:0xf bank_mask:0xf bound_ctrl:1
	v_pk_add_f32 v[56:57], v[56:57], v[58:59]
	s_nop 0
	v_add_f32_e32 v56, v56, v57
	v_add_f32_dpp v0, v0, v0 quad_perm:[2,3,0,1] row_mask:0xf bank_mask:0xf bound_ctrl:1
	s_nop 0
	v_add_f32_dpp v56, v56, v56 quad_perm:[1,0,3,2] row_mask:0xf bank_mask:0xf bound_ctrl:1
	v_add_f32_dpp v0, v0, v0 row_half_mirror row_mask:0xf bank_mask:0xf bound_ctrl:1
	s_nop 0
	v_add_f32_dpp v56, v56, v56 quad_perm:[2,3,0,1] row_mask:0xf bank_mask:0xf bound_ctrl:1
	v_mov_b32_dpp v45, v0 row_ror:8 row_mask:0xf bank_mask:0xf bound_ctrl:1
	s_nop 0
	v_add_f32_dpp v56, v56, v56 row_half_mirror row_mask:0xf bank_mask:0xf bound_ctrl:1
	s_nop 1
	v_add_f32_dpp v56, v56, v56 row_ror:8 row_mask:0xf bank_mask:0xf bound_ctrl:1
	s_nop 0
	v_fma_f32 v55, -v165, v56, v55
	v_mul_f32_e32 v56, v164, v55
	v_pk_mul_f32 v[58:59], v[76:77], v[56:57] op_sel_hi:[1,0]
	v_pk_mul_f32 v[60:61], v[78:79], v[56:57] op_sel_hi:[1,0]
	v_pk_fma_f32 v[46:47], v[164:165], v[46:47], v[58:59] op_sel:[1,0,0]
	v_pk_fma_f32 v[52:53], v[164:165], v[52:53], v[60:61] op_sel:[1,0,0]
	v_pk_mul_f32 v[58:59], v[74:75], v[56:57] op_sel_hi:[1,0]
	v_pk_mul_f32 v[56:57], v[72:73], v[56:57] op_sel_hi:[1,0]
	v_pk_fma_f32 v[50:51], v[164:165], v[50:51], v[58:59] op_sel:[1,0,0]
	v_pk_fma_f32 v[48:49], v[164:165], v[48:49], v[56:57] op_sel:[1,0,0]
	v_pk_mul_f32 v[56:57], v[84:85], v[46:47]
	v_pk_mul_f32 v[58:59], v[86:87], v[52:53]
	v_pk_fma_f32 v[56:57], v[48:49], v[80:81], v[56:57]
	v_pk_fma_f32 v[58:59], v[50:51], v[82:83], v[58:59]
	s_nop 0
	v_pk_mul_f32 v[60:61], v[94:95], v[52:53]
	v_pk_add_f32 v[56:57], v[56:57], v[58:59]
	v_pk_mul_f32 v[58:59], v[92:93], v[46:47]
	v_pk_fma_f32 v[60:61], v[50:51], v[90:91], v[60:61]
	v_pk_fma_f32 v[58:59], v[48:49], v[88:89], v[58:59]
	v_add_f32_e32 v55, v56, v57
	v_pk_add_f32 v[58:59], v[58:59], v[60:61]
	s_nop 0
	v_add_f32_e32 v57, v58, v59
	v_add_f32_dpp v55, v55, v55 quad_perm:[1,0,3,2] row_mask:0xf bank_mask:0xf bound_ctrl:1
	s_nop 0
	v_add_f32_dpp v57, v57, v57 quad_perm:[1,0,3,2] row_mask:0xf bank_mask:0xf bound_ctrl:1
	v_add_f32_dpp v55, v55, v55 quad_perm:[2,3,0,1] row_mask:0xf bank_mask:0xf bound_ctrl:1
	s_nop 0
	v_add_f32_dpp v57, v57, v57 quad_perm:[2,3,0,1] row_mask:0xf bank_mask:0xf bound_ctrl:1
	v_add_f32_dpp v55, v55, v55 row_half_mirror row_mask:0xf bank_mask:0xf bound_ctrl:1
	s_nop 0
	v_add_f32_dpp v57, v57, v57 row_half_mirror row_mask:0xf bank_mask:0xf bound_ctrl:1
	v_mov_b32_dpp v56, v55 row_ror:8 row_mask:0xf bank_mask:0xf bound_ctrl:1
	s_nop 0
	v_add_f32_dpp v57, v57, v57 row_ror:8 row_mask:0xf bank_mask:0xf bound_ctrl:1
	s_nop 0
	v_fma_f32 v57, -v167, v57, v170
	v_mul_f32_e32 v58, v166, v57
	v_pk_mul_f32 v[60:61], v[92:93], v[58:59] op_sel_hi:[1,0]
	v_pk_mul_f32 v[62:63], v[94:95], v[58:59] op_sel_hi:[1,0]
	v_pk_fma_f32 v[60:61], v[166:167], v[46:47], v[60:61] op_sel:[1,0,0]
	v_pk_fma_f32 v[52:53], v[166:167], v[52:53], v[62:63] op_sel:[1,0,0]
	v_pk_mul_f32 v[46:47], v[90:91], v[58:59] op_sel_hi:[1,0]
	v_pk_mul_f32 v[58:59], v[88:89], v[58:59] op_sel_hi:[1,0]
	s_nop 0
	v_pk_fma_f32 v[62:63], v[166:167], v[48:49], v[58:59] op_sel:[1,0,0]
	v_pk_fma_f32 v[48:49], v[166:167], v[50:51], v[46:47] op_sel:[1,0,0]
	v_pk_mul_f32 v[46:47], v[100:101], v[60:61]
	v_pk_mul_f32 v[50:51], v[102:103], v[52:53]
	v_pk_fma_f32 v[46:47], v[62:63], v[96:97], v[46:47]
	v_pk_fma_f32 v[50:51], v[48:49], v[98:99], v[50:51]
	s_nop 0
	v_pk_add_f32 v[46:47], v[46:47], v[50:51]
	s_nop 0
	v_pk_mul_f32 v[50:51], v[150:151], v[52:53]
	v_add_f32_e32 v46, v46, v47
	v_pk_fma_f32 v[50:51], v[48:49], v[118:119], v[50:51]
	s_nop 0
	v_add_f32_dpp v46, v46, v46 quad_perm:[1,0,3,2] row_mask:0xf bank_mask:0xf bound_ctrl:1
	s_nop 1
	v_add_f32_dpp v46, v46, v46 quad_perm:[2,3,0,1] row_mask:0xf bank_mask:0xf bound_ctrl:1
	s_nop 1
	v_add_f32_dpp v57, v46, v46 row_half_mirror row_mask:0xf bank_mask:0xf bound_ctrl:1
	v_pk_mul_f32 v[46:47], v[148:149], v[60:61]
	s_nop 0
	v_pk_fma_f32 v[46:47], v[62:63], v[116:117], v[46:47]
	v_mov_b32_dpp v58, v57 row_ror:8 row_mask:0xf bank_mask:0xf bound_ctrl:1
	v_pk_add_f32 v[46:47], v[46:47], v[50:51]
	s_nop 0
	v_add_f32_e32 v46, v46, v47
	s_nop 1
	v_add_f32_dpp v46, v46, v46 quad_perm:[1,0,3,2] row_mask:0xf bank_mask:0xf bound_ctrl:1
	s_nop 1
	v_add_f32_dpp v46, v46, v46 quad_perm:[2,3,0,1] row_mask:0xf bank_mask:0xf bound_ctrl:1
	s_nop 1
	v_add_f32_dpp v46, v46, v46 row_half_mirror row_mask:0xf bank_mask:0xf bound_ctrl:1
	s_nop 1
	v_add_f32_dpp v46, v46, v46 row_ror:8 row_mask:0xf bank_mask:0xf bound_ctrl:1
	s_nop 0
	v_fma_f32 v46, -v105, v46, v171
	v_mul_f32_e32 v64, v104, v46
	v_pk_mul_f32 v[50:51], v[148:149], v[64:65] op_sel_hi:[1,0]
	v_pk_mul_f32 v[46:47], v[150:151], v[64:65] op_sel_hi:[1,0]
	v_pk_fma_f32 v[50:51], v[104:105], v[60:61], v[50:51] op_sel:[1,0,0]
	v_pk_fma_f32 v[46:47], v[104:105], v[52:53], v[46:47] op_sel:[1,0,0]
	v_pk_mul_f32 v[52:53], v[116:117], v[64:65] op_sel_hi:[1,0]
	v_pk_mul_f32 v[60:61], v[118:119], v[64:65] op_sel_hi:[1,0]
	v_pk_fma_f32 v[52:53], v[104:105], v[62:63], v[52:53] op_sel:[1,0,0]
	v_pk_fma_f32 v[48:49], v[104:105], v[48:49], v[60:61] op_sel:[1,0,0]
	v_pk_mul_f32 v[60:61], v[156:157], v[50:51]
	v_pk_mul_f32 v[62:63], v[158:159], v[46:47]
	v_pk_fma_f32 v[60:61], v[52:53], v[152:153], v[60:61]
	v_pk_fma_f32 v[62:63], v[48:49], v[154:155], v[62:63]
	s_nop 0
	v_pk_add_f32 v[60:61], v[60:61], v[62:63]
	s_nop 0
	v_add_f32_e32 v59, v60, v61
	s_nop 1
	v_add_f32_dpp v59, v59, v59 quad_perm:[1,0,3,2] row_mask:0xf bank_mask:0xf bound_ctrl:1
	s_nop 1
	v_add_f32_dpp v59, v59, v59 quad_perm:[2,3,0,1] row_mask:0xf bank_mask:0xf bound_ctrl:1
	s_nop 1
	v_add_f32_dpp v59, v59, v59 row_half_mirror row_mask:0xf bank_mask:0xf bound_ctrl:1
	s_nop 1
	v_mov_b32_dpp v60, v59 row_ror:8 row_mask:0xf bank_mask:0xf bound_ctrl:1
	s_and_saveexec_b64 s[24:25], vcc
	s_cbranch_execz .Lsu_gd_st
	v_add_f32_e32 v0, v0, v45
	v_cmp_eq_u32_e32 vcc, 0, v54
	s_lshl_b32 s1, s1, 7
	v_or_b32_e32 v62, s2, v54
	v_mov_b32_e32 v63, v1
	v_readlane_b32 s2, v251, 47
	v_add_f32_e32 v55, v55, v56
	v_cndmask_b32_e32 v0, 0, v0, vcc
	v_cmp_eq_u32_e32 vcc, 1, v54
	v_lshlrev_b64 v[62:63], 12, v[62:63]
	v_readlane_b32 s3, v251, 48
	v_add_u32_e32 v64, s1, v44
	v_add_f32_e32 v57, v57, v58
	v_cndmask_b32_e32 v0, v0, v55, vcc
	v_cmp_eq_u32_e32 vcc, 2, v54
	v_lshl_add_u64 v[62:63], s[2:3], 0, v[62:63]
	v_ashrrev_i32_e32 v65, 31, v64
	v_add_f32_e32 v44, v59, v60
	v_cndmask_b32_e32 v0, v0, v57, vcc
	v_cmp_eq_u32_e32 vcc, 3, v54
	v_lshl_add_u64 v[62:63], v[64:65], 2, v[62:63]
	s_nop 0
	v_cndmask_b32_e32 v0, v0, v44, vcc
	global_store_dword v[62:63], v0, off
.Lsu_gd_st:
	s_or_b64 exec, exec, s[24:25]
	v_lshl_add_u64 v[42:43], v[42:43], 2, s[40:41]
	s_mov_b64 s[2:3], 0
	global_store_dword v[42:43], v50, off
	global_store_dword v[42:43], v51, off offset:512
	global_store_dword v[42:43], v46, off offset:1024
	global_store_dword v[42:43], v47, off offset:1536
	global_store_dword v[42:43], v52, off offset:2048
	global_store_dword v[42:43], v53, off offset:2560
	global_store_dword v[42:43], v48, off offset:3072
	global_store_dword v[42:43], v49, off offset:3584
	s_add_i32 s13, s13, 1
	s_andn2_b64 vcc, exec, s[94:95]
	s_cbranch_vccnz .LBB0_1789
.Lstga_1242:
	s_bitcmp1_b32 s13, 0
	s_cselect_b32 s0, 0x9900, 0
	s_add_i32 s0, s0, 0
	v_add_u32_e32 v0, s0, v122
	v_add_u32_e32 v0, 0x5400, v0
	v_add_u32_e32 v26, s0, v123
	v_cndmask_b32_e64 v0, v0, v26, s[6:7]
	v_add_u32_e32 v0, v0, v136
	s_waitcnt vmcnt(14)
	ds_write_b128 v0, v[2:5]
	v_add_u32_e32 v0, s0, v124
	v_add_u32_e32 v0, 0x5400, v0
	v_add_u32_e32 v26, s0, v125
	v_cndmask_b32_e64 v0, v0, v26, s[6:7]
	v_add_u32_e32 v0, v0, v137
	s_waitcnt vmcnt(13)
	ds_write_b128 v0, v[6:9]
	v_add_u32_e32 v0, s0, v126
	v_add_u32_e32 v0, 0x5400, v0
	v_add_u32_e32 v26, s0, v127
	v_cndmask_b32_e64 v0, v0, v26, s[6:7]
	v_add_u32_e32 v0, v0, v140
	s_waitcnt vmcnt(12)
	ds_write_b128 v0, v[10:13]
	v_add_u32_e32 v0, s0, v128
	v_add_u32_e32 v0, 0x5400, v0
	v_add_u32_e32 v26, s0, v129
	v_cndmask_b32_e64 v0, v0, v26, s[6:7]
	v_add_u32_e32 v0, v0, v141
	s_waitcnt vmcnt(11)
	ds_write_b128 v0, v[14:17]
	v_add_u32_e32 v0, s0, v133
	s_mov_b64 s[2:3], 0
	s_and_saveexec_b64 s[4:5], s[8:9]
	s_xor_b64 s[24:25], exec, s[4:5]
	s_cbranch_execz .Lstga_1791
	s_and_saveexec_b64 s[4:5], s[34:35]
	s_xor_b64 s[30:31], exec, s[4:5]
	v_add_u32_e32 v0, s0, v131
	s_mov_b64 s[2:3], exec
	v_add_u32_e32 v0, 0x5400, v0
	s_or_b64 exec, exec, s[30:31]
	s_and_b64 s[2:3], s[2:3], exec
	s_or_saveexec_b64 s[24:25], s[24:25]
	v_mov_b32_e32 v26, v130
	s_xor_b64 exec, exec, s[24:25]
	s_cbranch_execnz .Lstga_1792

.Lstga_1247:
	v_add_u32_e32 v26, v26, v107
	v_lshl_add_u32 v0, v26, 4, v0
	s_waitcnt vmcnt(10)
	ds_write_b128 v0, v[18:21]
	s_or_b64 exec, exec, s[24:25]
	s_and_saveexec_b64 s[2:3], s[58:59]
	s_cbranch_execnz .Lstga_1794
	s_branch .Lstga_1795

.Lstga_1794:
	v_add3_u32 v0, s0, v134, v135
	s_waitcnt vmcnt(9)
	ds_write_b128 v0, v[22:25]
.Lstga_1795:
	s_or_b64 exec, exec, s[2:3]
	s_branch .LBB0_1789
.Lsu_rw_fin:
	s_ashr_i32 s4, s0, 4
	s_ashr_i32 s1, s0, 6
	s_and_b32 s1, s1, -4
	s_lshl_b32 s0, s4, 6
	s_and_b32 s0, s0, 0x3c0
	s_add_i32 s2, s1, 0x2000
	v_pk_mul_f32 v[50:51], v[42:43], v[50:51]
	v_pk_fma_f32 v[50:51], v[44:45], v[52:53], v[50:51]
	s_nop 0
	v_add_f32_e32 v0, v50, v51
	s_nop 1
	v_add_f32_dpp v0, v0, v0 quad_perm:[1,0,3,2] row_mask:0xf bank_mask:0xf bound_ctrl:1
	s_nop 1
	v_add_f32_dpp v0, v0, v0 quad_perm:[2,3,0,1] row_mask:0xf bank_mask:0xf bound_ctrl:1
	s_nop 1
	v_add_f32_dpp v0, v0, v0 row_half_mirror row_mask:0xf bank_mask:0xf bound_ctrl:1
	s_nop 1
	v_add_f32_dpp v0, v0, v0 row_ror:8 row_mask:0xf bank_mask:0xf bound_ctrl:1
	s_nop 0
	v_pk_mul_f32 v[52:53], v[56:57], v[0:1] op_sel_hi:[1,0]
	v_pk_mul_f32 v[50:51], v[58:59], v[0:1] op_sel_hi:[1,0]
	s_nop 0
	v_pk_fma_f32 v[52:53], v[60:61], v[172:173], v[52:53] op_sel_hi:[1,0,1]
	v_pk_fma_f32 v[50:51], v[62:63], v[172:173], v[50:51] op_sel_hi:[1,0,1]
	s_nop 0
	v_pk_fma_f32 v[42:43], v[42:43], v[64:65], v[52:53]
	v_pk_fma_f32 v[44:45], v[44:45], v[66:67], v[50:51]
	s_nop 0
	v_pk_mul_f32 v[50:51], v[68:69], v[42:43]
	s_nop 0
	v_pk_fma_f32 v[50:51], v[44:45], v[70:71], v[50:51]
	s_nop 0
	v_add_f32_e32 v0, v50, v51
	s_nop 0
	v_pk_mul_f32 v[50:51], v[72:73], v[42:43]
	s_nop 0
	v_pk_fma_f32 v[50:51], v[44:45], v[74:75], v[50:51]
	v_add_f32_dpp v0, v0, v0 quad_perm:[1,0,3,2] row_mask:0xf bank_mask:0xf bound_ctrl:1
	v_add_f32_e32 v50, v50, v51
	s_nop 0
	v_add_f32_dpp v0, v0, v0 quad_perm:[2,3,0,1] row_mask:0xf bank_mask:0xf bound_ctrl:1
	v_add_f32_dpp v50, v50, v50 quad_perm:[1,0,3,2] row_mask:0xf bank_mask:0xf bound_ctrl:1
	s_nop 0
	v_add_f32_dpp v0, v0, v0 row_half_mirror row_mask:0xf bank_mask:0xf bound_ctrl:1
	v_add_f32_dpp v50, v50, v50 quad_perm:[2,3,0,1] row_mask:0xf bank_mask:0xf bound_ctrl:1
	s_nop 0
	v_mov_b32_dpp v49, v0 row_ror:8 row_mask:0xf bank_mask:0xf bound_ctrl:1
	v_add_f32_dpp v50, v50, v50 row_half_mirror row_mask:0xf bank_mask:0xf bound_ctrl:1
	s_nop 1
	v_add_f32_dpp v50, v50, v50 row_ror:8 row_mask:0xf bank_mask:0xf bound_ctrl:1
	s_nop 0
	v_pk_mul_f32 v[52:53], v[78:79], v[50:51] op_sel_hi:[1,0]
	v_pk_mul_f32 v[50:51], v[76:77], v[50:51] op_sel_hi:[1,0]
	s_nop 0
	v_pk_fma_f32 v[52:53], v[82:83], v[174:175], v[52:53] op_sel_hi:[1,0,1]
	v_pk_fma_f32 v[50:51], v[80:81], v[174:175], v[50:51] op_sel_hi:[1,0,1]
	s_nop 0
	v_pk_fma_f32 v[44:45], v[86:87], v[44:45], v[52:53]
	v_pk_fma_f32 v[42:43], v[84:85], v[42:43], v[50:51]
	s_nop 0
	v_pk_mul_f32 v[52:53], v[92:93], v[42:43]
	v_pk_mul_f32 v[50:51], v[88:89], v[42:43]
	v_pk_fma_f32 v[52:53], v[44:45], v[94:95], v[52:53]
	v_pk_fma_f32 v[50:51], v[44:45], v[90:91], v[50:51]
	v_add_f32_e32 v52, v52, v53
	v_add_f32_e32 v50, v50, v51
	s_nop 0
	v_add_f32_dpp v52, v52, v52 quad_perm:[1,0,3,2] row_mask:0xf bank_mask:0xf bound_ctrl:1
	v_add_f32_dpp v50, v50, v50 quad_perm:[1,0,3,2] row_mask:0xf bank_mask:0xf bound_ctrl:1
	s_nop 0
	v_add_f32_dpp v52, v52, v52 quad_perm:[2,3,0,1] row_mask:0xf bank_mask:0xf bound_ctrl:1
	v_add_f32_dpp v50, v50, v50 quad_perm:[2,3,0,1] row_mask:0xf bank_mask:0xf bound_ctrl:1
	s_nop 0
	v_add_f32_dpp v52, v52, v52 row_half_mirror row_mask:0xf bank_mask:0xf bound_ctrl:1
	v_add_f32_dpp v50, v50, v50 row_half_mirror row_mask:0xf bank_mask:0xf bound_ctrl:1
	s_nop 0
	v_add_f32_dpp v52, v52, v52 row_ror:8 row_mask:0xf bank_mask:0xf bound_ctrl:1
	s_nop 0
	v_pk_mul_f32 v[56:57], v[98:99], v[52:53] op_sel_hi:[1,0]
	v_pk_mul_f32 v[52:53], v[96:97], v[52:53] op_sel_hi:[1,0]
	s_nop 0
	v_pk_fma_f32 v[56:57], v[102:103], v[176:177], v[56:57] op_sel_hi:[1,0,1]
	v_pk_fma_f32 v[52:53], v[100:101], v[176:177], v[52:53] op_sel_hi:[1,0,1]
	s_nop 0
	v_pk_fma_f32 v[44:45], v[118:119], v[44:45], v[56:57]
	v_pk_fma_f32 v[42:43], v[116:117], v[42:43], v[52:53]
	v_mov_b32_dpp v51, v50 row_ror:8 row_mask:0xf bank_mask:0xf bound_ctrl:1
	s_nop 0
	v_pk_mul_f32 v[56:57], v[152:153], v[42:43]
	v_pk_mul_f32 v[52:53], v[148:149], v[42:43]
	v_pk_fma_f32 v[56:57], v[44:45], v[154:155], v[56:57]
	v_pk_fma_f32 v[52:53], v[44:45], v[150:151], v[52:53]
	v_add_f32_e32 v55, v56, v57
	v_add_f32_e32 v52, v52, v53
	s_nop 0
	v_add_f32_dpp v55, v55, v55 quad_perm:[1,0,3,2] row_mask:0xf bank_mask:0xf bound_ctrl:1
	v_add_f32_dpp v52, v52, v52 quad_perm:[1,0,3,2] row_mask:0xf bank_mask:0xf bound_ctrl:1
	s_nop 0
	v_add_f32_dpp v55, v55, v55 quad_perm:[2,3,0,1] row_mask:0xf bank_mask:0xf bound_ctrl:1
	v_add_f32_dpp v52, v52, v52 quad_perm:[2,3,0,1] row_mask:0xf bank_mask:0xf bound_ctrl:1
	s_nop 0
	v_add_f32_dpp v55, v55, v55 row_half_mirror row_mask:0xf bank_mask:0xf bound_ctrl:1
	v_add_f32_dpp v52, v52, v52 row_half_mirror row_mask:0xf bank_mask:0xf bound_ctrl:1
	s_nop 0
	v_add_f32_dpp v56, v55, v55 row_ror:8 row_mask:0xf bank_mask:0xf bound_ctrl:1
	s_nop 0
	v_pk_mul_f32 v[58:59], v[158:159], v[56:57] op_sel_hi:[1,0]
	v_pk_mul_f32 v[56:57], v[156:157], v[56:57] op_sel_hi:[1,0]
	s_nop 0
	v_pk_fma_f32 v[58:59], v[162:163], v[178:179], v[58:59] op_sel_hi:[1,0,1]
	v_pk_fma_f32 v[56:57], v[160:161], v[178:179], v[56:57] op_sel_hi:[1,0,1]
	s_nop 0
	v_pk_fma_f32 v[44:45], v[166:167], v[44:45], v[58:59]
	v_pk_fma_f32 v[42:43], v[164:165], v[42:43], v[56:57]
	v_mov_b32_dpp v53, v52 row_ror:8 row_mask:0xf bank_mask:0xf bound_ctrl:1
	s_nop 0
	v_pk_mul_f32 v[56:57], v[168:169], v[42:43]
	s_nop 0
	v_pk_fma_f32 v[56:57], v[44:45], v[170:171], v[56:57]
	s_nop 0
	v_add_f32_e32 v55, v56, v57
	s_nop 1
	v_add_f32_dpp v55, v55, v55 quad_perm:[1,0,3,2] row_mask:0xf bank_mask:0xf bound_ctrl:1
	s_nop 1
	v_add_f32_dpp v55, v55, v55 quad_perm:[2,3,0,1] row_mask:0xf bank_mask:0xf bound_ctrl:1
	s_nop 1
	v_add_f32_dpp v55, v55, v55 row_half_mirror row_mask:0xf bank_mask:0xf bound_ctrl:1
	s_nop 1
	v_mov_b32_dpp v56, v55 row_ror:8 row_mask:0xf bank_mask:0xf bound_ctrl:1
	s_and_saveexec_b64 s[24:25], vcc
	s_cbranch_execz .Lsu_rw_st
	v_add_f32_e32 v0, v0, v49
	v_cmp_eq_u32_e32 vcc, 0, v54
	v_add_f32_e32 v50, v50, v51
	v_add_f32_e32 v52, v52, v53
	v_cndmask_b32_e32 v0, 0, v0, vcc
	v_cmp_eq_u32_e32 vcc, 1, v54
	v_add_u32_e32 v58, s0, v48
	v_add_f32_e32 v48, v55, v56
	v_cndmask_b32_e32 v0, v0, v50, vcc
	v_cmp_eq_u32_e32 vcc, 2, v54
	v_readlane_b32 s0, v251, 37
	v_readlane_b32 s1, v251, 38
	v_cndmask_b32_e32 v0, v0, v52, vcc
	v_cmp_eq_u32_e32 vcc, 3, v54
	v_ashrrev_i32_e32 v59, 31, v58
	s_nop 0
	v_cndmask_b32_e32 v0, v0, v48, vcc
	v_or_b32_e32 v48, s2, v54
	v_ashrrev_i32_e32 v49, 31, v48
	v_lshlrev_b64 v[48:49], 12, v[48:49]
	v_lshl_add_u64 v[48:49], s[0:1], 0, v[48:49]
	v_lshl_add_u64 v[48:49], v[58:59], 2, v[48:49]
	global_store_dword v[48:49], v0, off
.Lsu_rw_st:
	s_or_b64 exec, exec, s[24:25]
	v_lshl_add_u64 v[46:47], v[46:47], 2, s[22:23]
	global_store_dwordx4 v[46:47], v[42:45], off
	s_add_i32 s13, s13, 1
	s_andn2_b64 vcc, exec, s[94:95]
	s_cbranch_vccnz .LBB0_1789
.Lstgb_1242:
	s_bitcmp1_b32 s13, 0
	s_cselect_b32 s0, 0x9900, 0
	s_add_i32 s0, s0, 0
	v_add_u32_e32 v0, s0, v122
	v_add_u32_e32 v0, 0x5400, v0
	v_add_u32_e32 v26, s0, v123
	v_cndmask_b32_e64 v0, v0, v26, s[6:7]
	v_add_u32_e32 v0, v0, v136
	s_waitcnt vmcnt(7)
	ds_write_b128 v0, v[2:5]
	v_add_u32_e32 v0, s0, v124
	v_add_u32_e32 v0, 0x5400, v0
	v_add_u32_e32 v26, s0, v125
	v_cndmask_b32_e64 v0, v0, v26, s[6:7]
	v_add_u32_e32 v0, v0, v137
	s_waitcnt vmcnt(6)
	ds_write_b128 v0, v[6:9]
	v_add_u32_e32 v0, s0, v126
	v_add_u32_e32 v0, 0x5400, v0
	v_add_u32_e32 v26, s0, v127
	v_cndmask_b32_e64 v0, v0, v26, s[6:7]
	v_add_u32_e32 v0, v0, v140
	s_waitcnt vmcnt(5)
	ds_write_b128 v0, v[10:13]
	v_add_u32_e32 v0, s0, v128
	v_add_u32_e32 v0, 0x5400, v0
	v_add_u32_e32 v26, s0, v129
	v_cndmask_b32_e64 v0, v0, v26, s[6:7]
	v_add_u32_e32 v0, v0, v141
	s_waitcnt vmcnt(4)
	ds_write_b128 v0, v[14:17]
	v_add_u32_e32 v0, s0, v133
	s_mov_b64 s[2:3], 0
	s_and_saveexec_b64 s[4:5], s[8:9]
	s_xor_b64 s[24:25], exec, s[4:5]
	s_cbranch_execz .Lstgb_1791
	s_and_saveexec_b64 s[4:5], s[34:35]
	s_xor_b64 s[30:31], exec, s[4:5]
	v_add_u32_e32 v0, s0, v131
	s_mov_b64 s[2:3], exec
	v_add_u32_e32 v0, 0x5400, v0
	s_or_b64 exec, exec, s[30:31]
	s_and_b64 s[2:3], s[2:3], exec
	s_or_saveexec_b64 s[24:25], s[24:25]
	v_mov_b32_e32 v26, v130
	s_xor_b64 exec, exec, s[24:25]
	s_cbranch_execnz .Lstgb_1792

.Lstgb_1247:
	v_add_u32_e32 v26, v26, v107
	v_lshl_add_u32 v0, v26, 4, v0
	s_waitcnt vmcnt(3)
	ds_write_b128 v0, v[18:21]
	s_or_b64 exec, exec, s[24:25]
	s_and_saveexec_b64 s[2:3], s[58:59]
	s_cbranch_execnz .Lstgb_1794
	s_branch .Lstgb_1795

.Lstgb_1794:
	v_add3_u32 v0, s0, v134, v135
	s_waitcnt vmcnt(2)
	ds_write_b128 v0, v[22:25]

.LBB0_1786:
	v_mov_b32_e32 v115, v138
	s_and_b32 s0, s56, 0xfc00
	s_add_i32 s0, s0, s51
	v_and_b32_e32 v54, 15, v115
	s_cmpk_gt_i32 s0, 0x7fff
	s_cbranch_scc0 .Lsu_rw_ld
	s_add_i32 s2, s0, 0xffff8000
	v_ashrrev_i32_e32 v0, 4, v115
	v_readlane_b32 s3, v251, 45
	s_lshr_b32 s46, s2, 5
	s_lshl_b64 s[24:25], s[46:47], 14
	v_add_u32_e32 v44, s3, v0
	v_ashrrev_i32_e32 v45, 31, v44
	v_lshlrev_b32_e32 v0, 10, v54
	v_lshl_add_u64 v[42:43], s[24:25], 0, v[44:45]
	v_readlane_b32 s24, v251, 57
	v_lshl_add_u64 v[42:43], v[42:43], 0, v[0:1]
	v_readlane_b32 s25, v251, 58
	s_bfe_u32 s1, s2, 0x30005
	s_lshr_b32 s2, s2, 6
	v_lshl_add_u64 v[56:57], v[42:43], 2, s[24:25]
	v_readlane_b32 s24, v251, 49
	s_and_b32 s4, s2, 0x1fffffc
	v_lshlrev_b32_e32 v0, 5, v54
	v_readlane_b32 s25, v251, 50
	s_add_i32 s2, s4, 0x2000
	s_lshl_b32 s3, s1, 3
	v_lshl_add_u64 v[104:105], s[24:25], 0, v[0:1]
	v_readlane_b32 s24, v251, 53
	v_readlane_b32 s25, v251, 54
	s_add_u32 s18, s19, s3
	s_mov_b32 s3, s47
	v_lshl_add_u64 v[152:153], s[24:25], 0, v[0:1]
	s_addc_u32 s30, s63, 0
	s_lshl_b64 s[24:25], s[2:3], 12
	s_lshl_b32 s3, s1, 9
	s_or_b32 s26, s24, s3
	s_mov_b32 s27, s25
	v_lshl_add_u64 v[60:61], v[104:105], 0, s[26:27]
	global_load_dword v46, v[56:57], off
	global_load_dword v47, v[56:57], off offset:512
	global_load_dword v52, v[56:57], off offset:1024
	global_load_dword v53, v[56:57], off offset:1536
	global_load_dword v48, v[56:57], off offset:2048
	global_load_dword v49, v[56:57], off offset:2560
	global_load_dword v50, v[56:57], off offset:3072
	global_load_dword v51, v[56:57], off offset:3584
	s_nop 0
	global_load_dwordx4 v[56:59], v[60:61], off offset:16
	s_nop 0
	global_load_dwordx4 v[60:63], v[60:61], off
	v_lshl_add_u64 v[160:161], v[44:45], 2, s[14:15]
	s_add_u32 s24, s18, s24
	v_lshl_add_u64 v[68:69], v[152:153], 0, s[26:27]
	v_lshl_add_u64 v[72:73], v[160:161], 0, s[26:27]
	s_addc_u32 s25, s30, s25
	global_load_dwordx4 v[64:67], v[68:69], off offset:16
	s_nop 0
	global_load_dwordx4 v[68:71], v[68:69], off
	s_add_i32 s46, s4, 0x2001
	global_load_dword v220, v[72:73], off
	global_load_dwordx2 v[162:163], v1, s[24:25]
	s_lshl_b64 s[24:25], s[46:47], 12
	s_or_b32 s26, s24, s3
	s_mov_b32 s27, s25
	v_lshl_add_u64 v[76:77], v[104:105], 0, s[26:27]
	global_load_dwordx4 v[72:75], v[76:77], off offset:16
	s_nop 0
	global_load_dwordx4 v[76:79], v[76:77], off
	s_add_u32 s24, s18, s24
	v_lshl_add_u64 v[84:85], v[152:153], 0, s[26:27]
	v_lshl_add_u64 v[88:89], v[160:161], 0, s[26:27]
	s_addc_u32 s25, s30, s25
	global_load_dwordx4 v[80:83], v[84:85], off offset:16
	s_nop 0
	global_load_dwordx4 v[84:87], v[84:85], off
	s_add_i32 s46, s4, 0x2002
	global_load_dword v55, v[88:89], off
	global_load_dwordx2 v[164:165], v1, s[24:25]
	s_lshl_b64 s[24:25], s[46:47], 12
	s_or_b32 s26, s24, s3
	s_mov_b32 s27, s25
	v_lshl_add_u64 v[92:93], v[104:105], 0, s[26:27]
	global_load_dwordx4 v[88:91], v[92:93], off offset:16
	s_nop 0
	global_load_dwordx4 v[92:95], v[92:93], off
	s_add_u32 s24, s18, s24
	v_lshl_add_u64 v[100:101], v[152:153], 0, s[26:27]
	v_lshl_add_u64 v[116:117], v[160:161], 0, s[26:27]
	s_addc_u32 s25, s30, s25
	global_load_dwordx4 v[96:99], v[100:101], off offset:16
	s_nop 0
	global_load_dwordx4 v[100:103], v[100:101], off
	s_add_i32 s46, s4, 0x2003
	global_load_dword v170, v[116:117], off
	global_load_dwordx2 v[166:167], v1, s[24:25]
	s_lshl_b64 s[4:5], s[46:47], 12
	s_or_b32 s24, s4, s3
	s_mov_b32 s25, s5
	v_lshl_add_u64 v[104:105], v[104:105], 0, s[24:25]
	global_load_dwordx4 v[116:119], v[104:105], off offset:16
	global_load_dwordx4 v[148:151], v[104:105], off
	v_lshl_add_u64 v[104:105], v[152:153], 0, s[24:25]
	s_add_u32 s4, s18, s4
	global_load_dwordx4 v[152:155], v[104:105], off offset:16
	global_load_dwordx4 v[156:159], v[104:105], off
	v_lshl_add_u64 v[104:105], v[160:161], 0, s[24:25]
	s_addc_u32 s5, s30, s5
	global_load_dword v171, v[104:105], off
	global_load_dwordx2 v[104:105], v1, s[4:5]
	s_add_i32 s13, s13, 1
.Lstgc_1242:
	s_bitcmp1_b32 s13, 0
	s_cselect_b32 s0, 0x9900, 0
	s_add_i32 s0, s0, 0
	v_add_u32_e32 v0, s0, v122
	v_add_u32_e32 v0, 0x5400, v0
	v_add_u32_e32 v26, s0, v123
	v_cndmask_b32_e64 v0, v0, v26, s[6:7]
	v_add_u32_e32 v0, v0, v136
	s_waitcnt vmcnt(37)
	ds_write_b128 v0, v[2:5]
	v_add_u32_e32 v0, s0, v124
	v_add_u32_e32 v0, 0x5400, v0
	v_add_u32_e32 v26, s0, v125
	v_cndmask_b32_e64 v0, v0, v26, s[6:7]
	v_add_u32_e32 v0, v0, v137
	s_waitcnt vmcnt(36)
	ds_write_b128 v0, v[6:9]
	v_add_u32_e32 v0, s0, v126
	v_add_u32_e32 v0, 0x5400, v0
	v_add_u32_e32 v26, s0, v127
	v_cndmask_b32_e64 v0, v0, v26, s[6:7]
	v_add_u32_e32 v0, v0, v140
	s_waitcnt vmcnt(35)
	ds_write_b128 v0, v[10:13]
	v_add_u32_e32 v0, s0, v128
	v_add_u32_e32 v0, 0x5400, v0
	v_add_u32_e32 v26, s0, v129
	v_cndmask_b32_e64 v0, v0, v26, s[6:7]
	v_add_u32_e32 v0, v0, v141
	s_waitcnt vmcnt(34)
	ds_write_b128 v0, v[14:17]
	v_add_u32_e32 v0, s0, v133
	s_mov_b64 s[2:3], 0
	s_and_saveexec_b64 s[4:5], s[8:9]
	s_xor_b64 s[24:25], exec, s[4:5]
	s_cbranch_execz .Lstgc_1791
	s_and_saveexec_b64 s[4:5], s[34:35]
	s_xor_b64 s[30:31], exec, s[4:5]
	v_add_u32_e32 v0, s0, v131
	s_mov_b64 s[2:3], exec
	v_add_u32_e32 v0, 0x5400, v0
	s_or_b64 exec, exec, s[30:31]
	s_and_b64 s[2:3], s[2:3], exec
	s_or_saveexec_b64 s[24:25], s[24:25]
	v_mov_b32_e32 v26, v130
	s_xor_b64 exec, exec, s[24:25]
	s_cbranch_execnz .Lstgc_1792

.Lstgc_1247:
	v_add_u32_e32 v26, v26, v107
	v_lshl_add_u32 v0, v26, 4, v0
	s_waitcnt vmcnt(33)
	ds_write_b128 v0, v[18:21]
	s_or_b64 exec, exec, s[24:25]
	s_and_saveexec_b64 s[2:3], s[58:59]
	s_cbranch_execnz .Lstgc_1794
	s_branch .Lstgc_1795

.Lstgc_1794:
	v_add3_u32 v0, s0, v134, v135
	s_waitcnt vmcnt(32)
	ds_write_b128 v0, v[22:25]

.Lsu_rw_ld:
	v_ashrrev_i32_e32 v0, 4, v115
	v_readlane_b32 s1, v251, 39
	s_ashr_i32 s4, s0, 4
	s_ashr_i32 s0, s0, 6
	v_add_u32_e32 v48, s1, v0
	s_ashr_i32 s5, s4, 31
	v_lshlrev_b32_e32 v42, 6, v48
	s_and_b32 s1, s0, -4
	s_lshl_b32 s0, s4, 6
	s_lshl_b64 s[4:5], s[4:5], 12
	v_ashrrev_i32_e32 v43, 31, v42
	v_lshl_add_u64 v[46:47], s[4:5], 0, v[42:43]
	v_readlane_b32 s4, v251, 31
	v_lshl_or_b32 v46, v54, 2, v46
	v_readlane_b32 s5, v251, 32
	v_lshlrev_b32_e32 v0, 4, v54
	s_add_i32 s2, s1, 0x2000
	v_lshl_add_u64 v[42:43], v[46:47], 2, s[4:5]
	v_readlane_b32 s4, v250, 3
	v_readlane_b32 s5, v250, 4
	s_and_b32 s0, s0, 0x3c0
	s_ashr_i32 s3, s2, 31
	v_lshl_add_u64 v[104:105], s[4:5], 0, v[0:1]
	v_readlane_b32 s4, v251, 35
	v_readlane_b32 s5, v251, 36
	global_load_dwordx4 v[42:45], v[42:43], off
	v_ashrrev_i32_e32 v49, 31, v48
	v_lshl_add_u64 v[152:153], s[4:5], 0, v[0:1]
	v_readlane_b32 s4, v251, 51
	v_readlane_b32 s5, v251, 52
	v_lshl_add_u64 v[164:165], v[48:49], 2, s[52:53]
	v_lshl_add_u64 v[168:169], s[16:17], 0, v[0:1]
	v_lshl_add_u64 v[156:157], s[4:5], 0, v[0:1]
	v_readlane_b32 s4, v250, 1
	v_readlane_b32 s5, v250, 2
	v_cmp_gt_u32_e32 vcc, 4, v54
	s_nop 0
	v_lshl_add_u64 v[158:159], s[4:5], 0, v[0:1]
	s_lshl_b64 s[4:5], s[2:3], 12
	s_lshl_b32 s3, s0, 2
	s_or_b32 s4, s4, s3
	v_lshl_add_u64 v[50:51], v[152:153], 0, s[4:5]
	global_load_dwordx4 v[50:53], v[50:51], off
	v_lshl_add_u64 v[64:65], v[104:105], 0, s[4:5]
	v_lshl_add_u64 v[56:57], v[156:157], 0, s[4:5]
	v_lshl_add_u64 v[60:61], v[158:159], 0, s[4:5]
	v_lshl_add_u64 v[66:67], v[164:165], 0, s[4:5]
	v_lshl_add_u64 v[68:69], v[168:169], 0, s[4:5]
	s_add_i32 s4, s1, 0x2001
	global_load_dwordx4 v[56:59], v[56:57], off
	s_nop 0
	global_load_dwordx4 v[60:63], v[60:61], off
	s_ashr_i32 s5, s4, 31
	global_load_dword v172, v[66:67], off
	s_nop 0
	global_load_dwordx4 v[64:67], v[64:65], off
	s_lshl_b64 s[4:5], s[4:5], 12
	global_load_dwordx4 v[68:71], v[68:69], off
	s_or_b32 s4, s4, s3
	v_lshl_add_u64 v[72:73], v[152:153], 0, s[4:5]
	global_load_dwordx4 v[72:75], v[72:73], off
	v_lshl_add_u64 v[76:77], v[156:157], 0, s[4:5]
	v_lshl_add_u64 v[80:81], v[158:159], 0, s[4:5]
	v_lshl_add_u64 v[84:85], v[164:165], 0, s[4:5]
	v_lshl_add_u64 v[88:89], v[168:169], 0, s[4:5]
	global_load_dwordx4 v[76:79], v[76:77], off
	s_nop 0
	global_load_dwordx4 v[80:83], v[80:81], off
	global_load_dword v174, v[84:85], off
	global_load_dwordx4 v[88:91], v[88:89], off
	v_lshl_add_u64 v[84:85], v[104:105], 0, s[4:5]
	s_add_i32 s4, s1, 0x2002
	s_ashr_i32 s5, s4, 31
	s_lshl_b64 s[4:5], s[4:5], 12
	s_or_b32 s4, s4, s3
	global_load_dwordx4 v[84:87], v[84:85], off
	v_lshl_add_u64 v[92:93], v[152:153], 0, s[4:5]
	global_load_dwordx4 v[92:95], v[92:93], off
	v_lshl_add_u64 v[96:97], v[156:157], 0, s[4:5]
	v_lshl_add_u64 v[100:101], v[158:159], 0, s[4:5]
	v_lshl_add_u64 v[116:117], v[164:165], 0, s[4:5]
	v_lshl_add_u64 v[148:149], v[168:169], 0, s[4:5]
	global_load_dwordx4 v[96:99], v[96:97], off
	s_nop 0
	global_load_dwordx4 v[100:103], v[100:101], off
	global_load_dword v176, v[116:117], off
	s_nop 0
	global_load_dwordx4 v[148:151], v[148:149], off
	v_lshl_add_u64 v[116:117], v[104:105], 0, s[4:5]
	s_add_i32 s4, s1, 0x2003
	s_ashr_i32 s5, s4, 31
	s_lshl_b64 s[4:5], s[4:5], 12
	s_or_b32 s4, s4, s3
	global_load_dwordx4 v[116:119], v[116:117], off
	v_lshl_add_u64 v[152:153], v[152:153], 0, s[4:5]
	global_load_dwordx4 v[152:155], v[152:153], off
	v_lshl_add_u64 v[156:157], v[156:157], 0, s[4:5]
	v_lshl_add_u64 v[160:161], v[158:159], 0, s[4:5]
	v_lshl_add_u64 v[164:165], v[164:165], 0, s[4:5]
	global_load_dwordx4 v[156:159], v[156:157], off
	s_nop 0
	global_load_dwordx4 v[160:163], v[160:161], off
	v_lshl_add_u64 v[104:105], v[104:105], 0, s[4:5]
	global_load_dword v178, v[164:165], off
	global_load_dwordx4 v[164:167], v[104:105], off
	v_lshl_add_u64 v[104:105], v[168:169], 0, s[4:5]
	global_load_dwordx4 v[168:171], v[104:105], off
	s_add_i32 s13, s13, 1
.Lstgd_1242:
	s_bitcmp1_b32 s13, 0
	s_cselect_b32 s0, 0x9900, 0
	s_add_i32 s0, s0, 0
	v_add_u32_e32 v0, s0, v122
	v_add_u32_e32 v0, 0x5400, v0
	v_add_u32_e32 v26, s0, v123
	v_cndmask_b32_e64 v0, v0, v26, s[6:7]
	v_add_u32_e32 v0, v0, v136
	s_waitcnt vmcnt(30)
	ds_write_b128 v0, v[2:5]
	v_add_u32_e32 v0, s0, v124
	v_add_u32_e32 v0, 0x5400, v0
	v_add_u32_e32 v26, s0, v125
	v_cndmask_b32_e64 v0, v0, v26, s[6:7]
	v_add_u32_e32 v0, v0, v137
	s_waitcnt vmcnt(29)
	ds_write_b128 v0, v[6:9]
	v_add_u32_e32 v0, s0, v126
	v_add_u32_e32 v0, 0x5400, v0
	v_add_u32_e32 v26, s0, v127
	v_cndmask_b32_e64 v0, v0, v26, s[6:7]
	v_add_u32_e32 v0, v0, v140
	s_waitcnt vmcnt(28)
	ds_write_b128 v0, v[10:13]
	v_add_u32_e32 v0, s0, v128
	v_add_u32_e32 v0, 0x5400, v0
	v_add_u32_e32 v26, s0, v129
	v_cndmask_b32_e64 v0, v0, v26, s[6:7]
	v_add_u32_e32 v0, v0, v141
	s_waitcnt vmcnt(27)
	ds_write_b128 v0, v[14:17]
	v_add_u32_e32 v0, s0, v133
	s_mov_b64 s[2:3], 0
	s_and_saveexec_b64 s[4:5], s[8:9]
	s_xor_b64 s[24:25], exec, s[4:5]
	s_cbranch_execz .Lstgd_1791
	s_and_saveexec_b64 s[4:5], s[34:35]
	s_xor_b64 s[30:31], exec, s[4:5]
	v_add_u32_e32 v0, s0, v131
	s_mov_b64 s[2:3], exec
	v_add_u32_e32 v0, 0x5400, v0
	s_or_b64 exec, exec, s[30:31]
	s_and_b64 s[2:3], s[2:3], exec
	s_or_saveexec_b64 s[24:25], s[24:25]
	v_mov_b32_e32 v26, v130
	s_xor_b64 exec, exec, s[24:25]
	s_cbranch_execnz .Lstgd_1792

.Lstgd_1247:
	v_add_u32_e32 v26, v26, v107
	v_lshl_add_u32 v0, v26, 4, v0
	s_waitcnt vmcnt(26)
	ds_write_b128 v0, v[18:21]
	s_or_b64 exec, exec, s[24:25]
	s_and_saveexec_b64 s[2:3], s[58:59]
	s_cbranch_execnz .Lstgd_1794
	s_branch .Lstgd_1795

.Lstgd_1794:
	v_add3_u32 v0, s0, v134, v135
	s_waitcnt vmcnt(25)
	ds_write_b128 v0, v[22:25]
